# v22 + mLSTM causal blocks: waves strictly below the diagonal skip the mask readlane/cndmask/perm code
# speedup vs baseline: 1.0024x; 1.0024x over previous
; #define LAS __attribute__((address_space(3)))
; DI void mlstm_phase(LAS unsigned char* lds, const bf16_t* proj, const float* gates, bf16_t* Hfw, bf16_t* Hbw, int G, int bid) {
;     ...
;                 const int t = 16 * wid + fr;
;                 bf16x8 qf[4];
; #pragma unroll
;                 for (int ks = 0; ks < 4; ++ks) qf[ks] = *(const LAS bf16x8*)(Qs + t * MQ_STRIDE + ks * 64 + fq * 16);
;                 const float Mt = sM[t], bt = sb[t];
;                 f32x4 nacc[5];
;                 {
;                     bf16x8 cf[2][4];
; #pragma unroll
;                     for (int dt = 0; dt < 5; ++dt) nacc[dt] = (f32x4){0.f, 0.f, 0.f, 0.f};
; #pragma unroll
;                     for (int db = 0; db < 3; ++db) {
; #pragma unroll
;                         for (int dt = 0; dt < 2; ++dt)
; #pragma unroll
;                             for (int ks = 0; ks < 4; ++ks) if (2 * db + dt < 5) cf[dt][ks] = *(const LAS bf16x8*)(Cs + (16 * (2 * db + dt) + fr) * MQ_STRIDE + ks * 64 + fq * 16);
;                         __builtin_amdgcn_sched_barrier(0);
; #pragma unroll
;                         for (int ks = 0; ks < 4; ++ks)
; #pragma unroll
;                             for (int dt = 0; dt < 2; ++dt) if (2 * db + dt < 5) nacc[2 * db + dt] = __builtin_amdgcn_mfma_f32_16x16x32_bf16(cf[dt][ks], qf[ks], nacc[2 * db + dt], 0, 0, 0);
;                         __builtin_amdgcn_sched_barrier(0);
;                     }
;                 }
;                 const float inter = __expf(mp - Mt);
; #pragma unroll
;                 for (int dt = 0; dt < 5; ++dt) nacc[dt] = nacc[dt] * inter;
.LBB0_843:
	s_waitcnt lgkmcnt(0)
	s_barrier
	v_lshl_add_u32 v0, v150, 2, s51
	ds_read_b128 v[116:119], v183
	ds_read_b128 v[112:115], v183 offset:64
	ds_read_b128 v[108:111], v183 offset:128
	ds_read_b128 v[100:103], v183 offset:192
	ds_read2st64_b32 v[2:3], v0 offset0:2 offset1:4
	ds_read_b128 v[84:87], v184
	ds_read_b128 v[88:91], v184 offset:64
	ds_read_b128 v[92:95], v184 offset:128
	ds_read_b128 v[96:99], v184 offset:192
	ds_read_b128 v[104:107], v184 offset:4352
	ds_read_b128 v[212:215], v184 offset:4416
	ds_read_b128 v[216:219], v184 offset:4480
	ds_read_b128 v[220:223], v184 offset:4544
	s_waitcnt lgkmcnt(7)
	v_mfma_f32_16x16x32_bf16 v[84:87], v[84:87], v[116:119], 0
	s_waitcnt lgkmcnt(3)
	v_mfma_f32_16x16x32_bf16 v[104:107], v[104:107], v[116:119], 0
	v_mfma_f32_16x16x32_bf16 v[84:87], v[88:91], v[112:115], v[84:87]
	s_waitcnt lgkmcnt(2)
	v_mfma_f32_16x16x32_bf16 v[88:91], v[212:215], v[112:115], v[104:107]
	v_mfma_f32_16x16x32_bf16 v[84:87], v[92:95], v[108:111], v[84:87]
	s_waitcnt lgkmcnt(1)
	v_mfma_f32_16x16x32_bf16 v[88:91], v[216:219], v[108:111], v[88:91]
	v_mfma_f32_16x16x32_bf16 v[84:87], v[96:99], v[100:103], v[84:87]
	s_waitcnt lgkmcnt(0)
	v_mfma_f32_16x16x32_bf16 v[88:91], v[220:223], v[100:103], v[88:91]
	ds_read_b128 v[92:95], v184 offset:8704
	ds_read_b128 v[96:99], v184 offset:8768
	ds_read_b128 v[104:107], v184 offset:8832
	ds_read_b128 v[212:215], v184 offset:8896
	ds_read_b128 v[216:219], v184 offset:13056
	ds_read_b128 v[220:223], v184 offset:13120
	ds_read_b128 v[224:227], v184 offset:13184
	ds_read_b128 v[228:231], v184 offset:13248
	s_waitcnt lgkmcnt(7)
	v_mfma_f32_16x16x32_bf16 v[92:95], v[92:95], v[116:119], 0
	s_waitcnt lgkmcnt(3)
	v_mfma_f32_16x16x32_bf16 v[216:219], v[216:219], v[116:119], 0
	v_mfma_f32_16x16x32_bf16 v[92:95], v[96:99], v[112:115], v[92:95]
	s_waitcnt lgkmcnt(2)
	v_mfma_f32_16x16x32_bf16 v[96:99], v[220:223], v[112:115], v[216:219]
	v_mfma_f32_16x16x32_bf16 v[92:95], v[104:107], v[108:111], v[92:95]
	s_waitcnt lgkmcnt(1)
	v_mfma_f32_16x16x32_bf16 v[96:99], v[224:227], v[108:111], v[96:99]
	v_mfma_f32_16x16x32_bf16 v[92:95], v[212:215], v[100:103], v[92:95]
	s_waitcnt lgkmcnt(0)
	v_mfma_f32_16x16x32_bf16 v[96:99], v[228:231], v[100:103], v[96:99]
	ds_read_b128 v[104:107], v184 offset:17408
	ds_read_b128 v[212:215], v184 offset:17472
	ds_read_b128 v[216:219], v184 offset:17536
	ds_read_b128 v[220:223], v184 offset:17600
	s_waitcnt lgkmcnt(3)
	v_mfma_f32_16x16x32_bf16 v[104:107], v[104:107], v[116:119], 0
	s_waitcnt lgkmcnt(2)
	v_mfma_f32_16x16x32_bf16 v[104:107], v[212:215], v[112:115], v[104:107]
	s_waitcnt lgkmcnt(1)
	v_mfma_f32_16x16x32_bf16 v[104:107], v[216:219], v[108:111], v[104:107]
	s_waitcnt lgkmcnt(0)
	v_mfma_f32_16x16x32_bf16 v[104:107], v[220:223], v[100:103], v[104:107]
	v_sub_f32_e32 v0, v142, v2
	v_mul_f32_e32 v0, 0x3fb8aa3b, v0
	v_exp_f32_e32 v0, v0
	s_andn2_b64 vcc, exec, s[24:25]
	v_pk_mul_f32 v[84:85], v[0:1], v[84:85] op_sel_hi:[0,1]
	v_pk_mul_f32 v[86:87], v[0:1], v[86:87] op_sel_hi:[0,1]
	v_pk_mul_f32 v[88:89], v[0:1], v[88:89] op_sel_hi:[0,1]
	v_pk_mul_f32 v[90:91], v[0:1], v[90:91] op_sel_hi:[0,1]
	v_pk_mul_f32 v[92:93], v[0:1], v[92:93] op_sel_hi:[0,1]
	v_pk_mul_f32 v[94:95], v[0:1], v[94:95] op_sel_hi:[0,1]
	v_pk_mul_f32 v[96:97], v[0:1], v[96:97] op_sel_hi:[0,1]
	v_pk_mul_f32 v[98:99], v[0:1], v[98:99] op_sel_hi:[0,1]
	v_pk_mul_f32 v[104:105], v[0:1], v[104:105] op_sel_hi:[0,1]
	v_pk_mul_f32 v[106:107], v[0:1], v[106:107] op_sel_hi:[0,1]
	v_lshl_add_u32 v0, v151, 2, s51
	s_cbranch_vccnz .LBB0_847
; #define LAS __attribute__((address_space(3)))
; DI void mlstm_phase(LAS unsigned char* lds, const bf16_t* proj, const float* gates, bf16_t* Hfw, bf16_t* Hbw, int G, int bid) {
;     ...
;                 for (int jj = 0; jj < 4; ++jj) {
;                     if (2 * jj <= wid) {
;                         f32x4 s0 = {0.f, 0.f, 0.f, 0.f}, s1 = s0;
;                         bf16x8 k0[4], k1[4], vfr[5];
;                         const int vr = 32 * jj + 4 * fq + (fr >> 2);
; #pragma unroll
;                         for (int ks = 0; ks < 4; ++ks) {
;                             k0[ks] = *(const LAS bf16x8*)(Ks + (32 * jj + fr) * MQ_STRIDE + ks * 64 + fq * 16);
;                             k1[ks] = *(const LAS bf16x8*)(Ks + (32 * jj + 16 + fr) * MQ_STRIDE + ks * 64 + fq * 16);
;                         }
;                         __builtin_amdgcn_sched_barrier(0);
; #pragma unroll
;                         for (int ks = 0; ks < 4; ++ks) {
;                             s0 = __builtin_amdgcn_mfma_f32_16x16x32_bf16(k0[ks], qf[ks], s0, 0, 0, 0);
;                             s1 = __builtin_amdgcn_mfma_f32_16x16x32_bf16(k1[ks], qf[ks], s1, 0, 0, 0);
;                         }
;                         __builtin_amdgcn_sched_barrier(0);
; #pragma unroll
;                         for (int dt = 0; dt < 5; ++dt) vfr[dt] = tr_pair(Vs + vr * MV_STRIDE + (16 * dt + 4 * (fr & 3)) * 2, Vs + (vr + 16) * MV_STRIDE + (16 * dt + 4 * (fr & 3)) * 2);
;                         const f32x4 a0 = *(const LAS f32x4*)(sa + 32 * jj + 4 * fq), a1 = *(const LAS f32x4*)(sa + 32 * jj + 16 + 4 * fq);
; #pragma unroll
;                         for (int i = 0; i < 4; ++i) {
;                             const int sA = 32 * jj + 4 * fq + i, sB = sA + 16;
;                             s0[i] = (sA <= t) ? s0[i] * __expf(a0[i] - Mt) : 0.f;
;                             s1[i] = (sB <= t) ? s1[i] * __expf(a1[i] - Mt) : 0.f;
;                         }
;                         u32x4 w; w.x = pk2(s0[0], s0[1]); w.y = pk2(s0[2], s0[3]); w.z = pk2(s1[0], s1[1]); w.w = pk2(s1[2], s1[3]);
;                         const bf16x8 pb = __builtin_bit_cast(bf16x8, w);
; #pragma unroll
;                         for (int dt = 0; dt < 5; ++dt) nacc[dt] = __builtin_amdgcn_mfma_f32_16x16x32_bf16(vfr[dt], pb, nacc[dt], 0, 0, 0);
;                     }
	ds_read_b128 v[212:215], v206 offset:34816
	ds_read_b128 v[216:219], v206 offset:34880
	ds_read_b128 v[220:223], v206 offset:39168
	ds_read_b128 v[224:227], v206 offset:39232
	ds_read_b128 v[228:231], v206 offset:34944
	ds_read_b128 v[232:235], v206 offset:35008
	ds_read_b128 v[236:239], v206 offset:39296
	ds_read_b128 v[240:243], v206 offset:39360
	s_waitcnt lgkmcnt(7)
	v_mfma_f32_16x16x32_bf16 v[212:215], v[212:215], v[116:119], 0
	ds_read_b128 v[244:247], v0
	ds_read_b64_tr_b16 v[248:249], v185
	ds_read_b128 v[126:129], v0 offset:64
	ds_read_b64_tr_b16 v[250:251], v185 offset:2560
	s_waitcnt lgkmcnt(10)
	v_mfma_f32_16x16x32_bf16 v[212:215], v[216:219], v[112:115], v[212:215]
	s_waitcnt lgkmcnt(3)
	v_sub_f32_e32 v125, v244, v2
	v_mul_f32_e32 v125, 0x3fb8aa3b, v125
	v_exp_f32_e32 v125, v125
	v_mfma_f32_16x16x32_bf16 v[216:219], v[220:223], v[116:119], 0
	v_sub_f32_e32 v135, v245, v2
	v_mul_f32_e32 v135, 0x3fb8aa3b, v135
	v_exp_f32_e32 v135, v135
	v_mfma_f32_16x16x32_bf16 v[212:215], v[228:231], v[108:111], v[212:215]
	v_sub_f32_e32 v147, v246, v2
	v_mul_f32_e32 v147, 0x3fb8aa3b, v147
	s_waitcnt lgkmcnt(1)
	v_sub_f32_e32 v126, v126, v2
	v_mfma_f32_16x16x32_bf16 v[216:219], v[224:227], v[112:115], v[216:219]
	v_sub_f32_e32 v127, v127, v2
	v_mul_f32_e32 v126, 0x3fb8aa3b, v126
	v_readlane_b32 s92, v254, 1
	v_mfma_f32_16x16x32_bf16 v[212:215], v[232:235], v[100:103], v[212:215]
	v_mul_f32_e32 v127, 0x3fb8aa3b, v127
	v_readlane_b32 s93, v254, 2
	v_exp_f32_e32 v126, v126
	v_mfma_f32_16x16x32_bf16 v[216:219], v[236:239], v[108:111], v[216:219]
	v_exp_f32_e32 v127, v127
	s_nop 2
	v_mul_f32_e32 v125, v212, v125
	v_exp_f32_e32 v212, v147
	v_sub_f32_e32 v147, v247, v2
	v_mul_f32_e32 v147, 0x3fb8aa3b, v147
	v_mul_f32_e32 v135, v213, v135
	v_exp_f32_e32 v213, v147
	v_mfma_f32_16x16x32_bf16 v[216:219], v[240:243], v[100:103], v[216:219]
	s_and_b64 vcc, exec, s[26:27]
	s_cbranch_vccnz .Lum0
	v_cndmask_b32_e64 v125, v125, 0, s[92:93]
	v_readlane_b32 s92, v254, 22
	v_readlane_b32 s93, v254, 23
	v_sub_f32_e32 v128, v128, v2
	v_sub_f32_e32 v129, v129, v2
	v_cndmask_b32_e64 v135, 0, v135, s[92:93]
	v_pk_mul_f32 v[212:213], v[214:215], v[212:213]
	v_readlane_b32 s92, v254, 58
	v_mul_f32_e32 v128, 0x3fb8aa3b, v128
	v_mul_f32_e32 v129, 0x3fb8aa3b, v129
	v_pk_mul_f32 v[216:217], v[216:217], v[126:127]
	v_cvt_pk_bf16_f32 v126, v125, v135
	v_cvt_pk_bf16_f32 v125, v212, v213
	v_readlane_b32 s93, v254, 59
	v_exp_f32_e32 v128, v128
	v_exp_f32_e32 v129, v129
	v_cndmask_b32_e64 v127, v125, 0, s[92:93]
	v_readlane_b32 s92, v254, 56
	v_lshrrev_b32_e32 v125, 16, v125
	v_readlane_b32 s93, v254, 57
	v_pk_mul_f32 v[214:215], v[218:219], v[128:129]
	s_nop 0
	v_cndmask_b32_e64 v125, v125, 0, s[92:93]
	v_readlane_b32 s92, v255, 24
	v_perm_b32 v127, v125, v127, s45
	v_cvt_pk_bf16_f32 v125, v216, v217
	v_readlane_b32 s93, v255, 25
	s_nop 1
	v_cndmask_b32_e64 v128, v125, 0, s[92:93]
	v_readlane_b32 s92, v254, 54
	v_lshrrev_b32_e32 v125, 16, v125
	v_readlane_b32 s93, v254, 55
	s_nop 1
	v_cndmask_b32_e64 v125, v125, 0, s[92:93]
	v_perm_b32 v128, v125, v128, s45
	v_cvt_pk_bf16_f32 v125, v214, v215
	ds_read_b64_tr_b16 v[214:215], v185 offset:2592
	ds_read_b64_tr_b16 v[212:213], v185 offset:32
	ds_read_b64_tr_b16 v[216:217], v185 offset:64
	ds_read_b64_tr_b16 v[220:221], v185 offset:96
	ds_read_b64_tr_b16 v[218:219], v185 offset:2624
	ds_read_b64_tr_b16 v[224:225], v185 offset:128
	ds_read_b64_tr_b16 v[222:223], v185 offset:2656
	ds_read_b64_tr_b16 v[226:227], v185 offset:2688
	v_readlane_b32 s92, v255, 7
	v_readlane_b32 s93, v255, 8
	s_nop 1
	v_cndmask_b32_e64 v129, v125, 0, s[92:93]
	v_readlane_b32 s92, v255, 5
	v_lshrrev_b32_e32 v125, 16, v125
	v_readlane_b32 s93, v255, 6
	s_nop 1
	v_cndmask_b32_e64 v125, v125, 0, s[92:93]
	v_perm_b32 v129, v125, v129, s45
.Lum0_join:
	s_waitcnt lgkmcnt(8)
	s_nop 0
	v_mfma_f32_16x16x32_bf16 v[84:87], v[248:251], v[126:129], v[84:87]
	s_waitcnt lgkmcnt(6)
	v_mfma_f32_16x16x32_bf16 v[88:91], v[212:215], v[126:129], v[88:91]
	s_waitcnt lgkmcnt(3)
	v_mfma_f32_16x16x32_bf16 v[92:95], v[216:219], v[126:129], v[92:95]
	s_waitcnt lgkmcnt(1)
	v_mfma_f32_16x16x32_bf16 v[96:99], v[220:223], v[126:129], v[96:99]
	s_waitcnt lgkmcnt(0)
	v_mfma_f32_16x16x32_bf16 v[104:107], v[224:227], v[126:129], v[104:107]
	s_andn2_b64 vcc, exec, s[26:27]
	s_cbranch_vccz .LBB0_848

; #define LAS __attribute__((address_space(3)))
; DI void mlstm_phase(LAS unsigned char* lds, const bf16_t* proj, const float* gates, bf16_t* Hfw, bf16_t* Hbw, int G, int bid) {
;     ...
;                 for (int jj = 0; jj < 4; ++jj) {
;                     if (2 * jj <= wid) {
;                         f32x4 s0 = {0.f, 0.f, 0.f, 0.f}, s1 = s0;
;                         bf16x8 k0[4], k1[4], vfr[5];
;                         const int vr = 32 * jj + 4 * fq + (fr >> 2);
; #pragma unroll
;                         for (int ks = 0; ks < 4; ++ks) {
;                             k0[ks] = *(const LAS bf16x8*)(Ks + (32 * jj + fr) * MQ_STRIDE + ks * 64 + fq * 16);
;                             k1[ks] = *(const LAS bf16x8*)(Ks + (32 * jj + 16 + fr) * MQ_STRIDE + ks * 64 + fq * 16);
;                         }
;                         __builtin_amdgcn_sched_barrier(0);
; #pragma unroll
;                         for (int ks = 0; ks < 4; ++ks) {
;                             s0 = __builtin_amdgcn_mfma_f32_16x16x32_bf16(k0[ks], qf[ks], s0, 0, 0, 0);
;                             s1 = __builtin_amdgcn_mfma_f32_16x16x32_bf16(k1[ks], qf[ks], s1, 0, 0, 0);
;                         }
;                         __builtin_amdgcn_sched_barrier(0);
; #pragma unroll
;                         for (int dt = 0; dt < 5; ++dt) vfr[dt] = tr_pair(Vs + vr * MV_STRIDE + (16 * dt + 4 * (fr & 3)) * 2, Vs + (vr + 16) * MV_STRIDE + (16 * dt + 4 * (fr & 3)) * 2);
;                         const f32x4 a0 = *(const LAS f32x4*)(sa + 32 * jj + 4 * fq), a1 = *(const LAS f32x4*)(sa + 32 * jj + 16 + 4 * fq);
; #pragma unroll
;                         for (int i = 0; i < 4; ++i) {
;                             const int sA = 32 * jj + 4 * fq + i, sB = sA + 16;
;                             s0[i] = (sA <= t) ? s0[i] * __expf(a0[i] - Mt) : 0.f;
;                             s1[i] = (sB <= t) ? s1[i] * __expf(a1[i] - Mt) : 0.f;
;                         }
;                         u32x4 w; w.x = pk2(s0[0], s0[1]); w.y = pk2(s0[2], s0[3]); w.z = pk2(s1[0], s1[1]); w.w = pk2(s1[2], s1[3]);
;                         const bf16x8 pb = __builtin_bit_cast(bf16x8, w);
; #pragma unroll
;                         for (int dt = 0; dt < 5; ++dt) nacc[dt] = __builtin_amdgcn_mfma_f32_16x16x32_bf16(vfr[dt], pb, nacc[dt], 0, 0, 0);
;                     }
.LBB0_846:
	ds_read_b128 v[126:129], v206 offset:52224
	ds_read_b128 v[212:215], v206 offset:52288
	ds_read_b128 v[216:219], v206 offset:56576
	ds_read_b128 v[220:223], v206 offset:56640
	ds_read_b128 v[224:227], v206 offset:52352
	ds_read_b128 v[228:231], v206 offset:52416
	ds_read_b128 v[232:235], v206 offset:56704
	ds_read_b128 v[236:239], v206 offset:56768
	ds_read_b128 v[240:243], v0 offset:256
	ds_read_b64_tr_b16 v[246:247], v190 offset:2560
	ds_read_b64_tr_b16 v[244:245], v190
	ds_read_b128 v[248:251], v0 offset:320
	s_waitcnt lgkmcnt(11)
	v_mfma_f32_16x16x32_bf16 v[126:129], v[126:129], v[116:119], 0
	s_waitcnt lgkmcnt(3)
	v_sub_f32_e32 v125, v240, v2
	v_mul_f32_e32 v125, 0x3fb8aa3b, v125
	v_exp_f32_e32 v240, v125
	s_waitcnt lgkmcnt(0)
	v_sub_f32_e32 v125, v248, v2
	v_mfma_f32_16x16x32_bf16 v[126:129], v[212:215], v[112:115], v[126:129]
	v_mul_f32_e32 v125, 0x3fb8aa3b, v125
	v_exp_f32_e32 v248, v125
	v_sub_f32_e32 v125, v241, v2
	v_mfma_f32_16x16x32_bf16 v[216:219], v[216:219], v[116:119], 0
	v_mul_f32_e32 v125, 0x3fb8aa3b, v125
	v_exp_f32_e32 v241, v125
	v_sub_f32_e32 v125, v249, v2
	v_mfma_f32_16x16x32_bf16 v[126:129], v[224:227], v[108:111], v[126:129]
	v_mul_f32_e32 v125, 0x3fb8aa3b, v125
	v_exp_f32_e32 v249, v125
	v_sub_f32_e32 v125, v242, v2
	v_mfma_f32_16x16x32_bf16 v[212:215], v[220:223], v[112:115], v[216:219]
	v_mul_f32_e32 v125, 0x3fb8aa3b, v125
	s_nop 1
	v_exp_f32_e32 v216, v125
	v_sub_f32_e32 v125, v250, v2
	v_mfma_f32_16x16x32_bf16 v[126:129], v[228:231], v[100:103], v[126:129]
	v_mul_f32_e32 v125, 0x3fb8aa3b, v125
	v_exp_f32_e32 v218, v125
	v_sub_f32_e32 v125, v243, v2
	v_mfma_f32_16x16x32_bf16 v[212:215], v[232:235], v[108:111], v[212:215]
	v_mul_f32_e32 v125, 0x3fb8aa3b, v125
	v_exp_f32_e32 v217, v125
	v_sub_f32_e32 v125, v251, v2
	v_mul_f32_e32 v125, 0x3fb8aa3b, v125
	v_pk_mul_f32 v[126:127], v[126:127], v[240:241]
	v_exp_f32_e32 v219, v125
	s_and_b64 vcc, exec, s[30:31]
	s_cbranch_vccnz .Lum2
	v_cvt_pk_bf16_f32 v125, v126, v127
	v_mfma_f32_16x16x32_bf16 v[212:215], v[236:239], v[100:103], v[212:215]
	v_cndmask_b32_e64 v126, v125, 0, s[60:61]
	v_lshrrev_b32_e32 v125, 16, v125
	v_pk_mul_f32 v[128:129], v[128:129], v[216:217]
	v_cndmask_b32_e64 v125, v125, 0, s[58:59]
	v_perm_b32 v126, v125, v126, s45
	v_cvt_pk_bf16_f32 v125, v128, v129
	v_cndmask_b32_e64 v127, v125, 0, s[68:69]
	v_lshrrev_b32_e32 v125, 16, v125
	v_pk_mul_f32 v[212:213], v[212:213], v[248:249]
	v_cndmask_b32_e64 v125, v125, 0, s[66:67]
	v_perm_b32 v127, v125, v127, s45
	v_cvt_pk_bf16_f32 v125, v212, v213
	v_cndmask_b32_e64 v128, v125, 0, s[64:65]
	v_lshrrev_b32_e32 v125, 16, v125
	v_pk_mul_f32 v[214:215], v[214:215], v[218:219]
	v_cndmask_b32_e64 v125, v125, 0, s[62:63]
	v_perm_b32 v128, v125, v128, s45
	v_cvt_pk_bf16_f32 v125, v214, v215
	ds_read_b64_tr_b16 v[214:215], v190 offset:2592
	ds_read_b64_tr_b16 v[212:213], v190 offset:32
	ds_read_b64_tr_b16 v[216:217], v190 offset:64
	ds_read_b64_tr_b16 v[220:221], v190 offset:96
	ds_read_b64_tr_b16 v[218:219], v190 offset:2624
	ds_read_b64_tr_b16 v[224:225], v190 offset:128
	ds_read_b64_tr_b16 v[222:223], v190 offset:2656
	ds_read_b64_tr_b16 v[226:227], v190 offset:2688
	v_cndmask_b32_e64 v129, v125, 0, s[72:73]
	v_lshrrev_b32_e32 v125, 16, v125
	v_cndmask_b32_e64 v125, v125, 0, s[70:71]
	v_perm_b32 v129, v125, v129, s45
.Lum2_join:
	s_nop 1
	v_mfma_f32_16x16x32_bf16 v[84:87], v[244:247], v[126:129], v[84:87]
	s_waitcnt lgkmcnt(6)
	v_mfma_f32_16x16x32_bf16 v[88:91], v[212:215], v[126:129], v[88:91]
	s_waitcnt lgkmcnt(3)
	v_mfma_f32_16x16x32_bf16 v[92:95], v[216:219], v[126:129], v[92:95]
	s_waitcnt lgkmcnt(1)
	v_mfma_f32_16x16x32_bf16 v[96:99], v[220:223], v[126:129], v[96:99]
	s_waitcnt lgkmcnt(0)
	v_mfma_f32_16x16x32_bf16 v[104:107], v[224:227], v[126:129], v[104:107]
	s_andn2_b64 vcc, exec, s[30:31]
	s_cbranch_vccz .LBB0_850
	s_branch .LBB0_851
.Lum0:
	v_sub_f32_e32 v128, v128, v2
	v_sub_f32_e32 v129, v129, v2
	v_pk_mul_f32 v[212:213], v[214:215], v[212:213]
	v_mul_f32_e32 v128, 0x3fb8aa3b, v128
	v_mul_f32_e32 v129, 0x3fb8aa3b, v129
	v_exp_f32_e32 v128, v128
	v_exp_f32_e32 v129, v129
	s_nop 1
	v_pk_mul_f32 v[216:217], v[216:217], v[126:127]
	v_cvt_pk_bf16_f32 v126, v125, v135
	v_cvt_pk_bf16_f32 v127, v212, v213
	v_pk_mul_f32 v[214:215], v[218:219], v[128:129]
	v_cvt_pk_bf16_f32 v128, v216, v217
	s_nop 0
	v_cvt_pk_bf16_f32 v129, v214, v215
	ds_read_b64_tr_b16 v[214:215], v185 offset:2592
	ds_read_b64_tr_b16 v[212:213], v185 offset:32
	ds_read_b64_tr_b16 v[216:217], v185 offset:64
	ds_read_b64_tr_b16 v[220:221], v185 offset:96
	ds_read_b64_tr_b16 v[218:219], v185 offset:2624
	ds_read_b64_tr_b16 v[224:225], v185 offset:128
	ds_read_b64_tr_b16 v[222:223], v185 offset:2656
	ds_read_b64_tr_b16 v[226:227], v185 offset:2688
	s_branch .Lum0_join
.Lum1:
	v_mfma_f32_16x16x32_bf16 v[212:215], v[236:239], v[100:103], v[212:215]
	v_cvt_pk_bf16_f32 v126, v126, v127
	v_pk_mul_f32 v[128:129], v[128:129], v[216:217]
	s_nop 0
	v_cvt_pk_bf16_f32 v127, v128, v129
	s_nop 4
	v_pk_mul_f32 v[212:213], v[212:213], v[248:249]
	v_pk_mul_f32 v[214:215], v[214:215], v[218:219]
	v_cvt_pk_bf16_f32 v128, v212, v213
	v_cvt_pk_bf16_f32 v129, v214, v215
	ds_read_b64_tr_b16 v[214:215], v188 offset:2592
	ds_read_b64_tr_b16 v[212:213], v188 offset:32
	ds_read_b64_tr_b16 v[216:217], v188 offset:64
	ds_read_b64_tr_b16 v[220:221], v188 offset:96
	ds_read_b64_tr_b16 v[218:219], v188 offset:2624
	ds_read_b64_tr_b16 v[224:225], v188 offset:128
	ds_read_b64_tr_b16 v[222:223], v188 offset:2656
	ds_read_b64_tr_b16 v[226:227], v188 offset:2688
	s_branch .Lum1_join
.Lum2:
	v_mfma_f32_16x16x32_bf16 v[212:215], v[236:239], v[100:103], v[212:215]
	v_cvt_pk_bf16_f32 v126, v126, v127
	v_pk_mul_f32 v[128:129], v[128:129], v[216:217]
	s_nop 0
	v_cvt_pk_bf16_f32 v127, v128, v129
	s_nop 4
	v_pk_mul_f32 v[212:213], v[212:213], v[248:249]
	v_pk_mul_f32 v[214:215], v[214:215], v[218:219]
	v_cvt_pk_bf16_f32 v128, v212, v213
	v_cvt_pk_bf16_f32 v129, v214, v215
	ds_read_b64_tr_b16 v[214:215], v190 offset:2592
	ds_read_b64_tr_b16 v[212:213], v190 offset:32
	ds_read_b64_tr_b16 v[216:217], v190 offset:64
	ds_read_b64_tr_b16 v[220:221], v190 offset:96
	ds_read_b64_tr_b16 v[218:219], v190 offset:2624
	ds_read_b64_tr_b16 v[224:225], v190 offset:128
	ds_read_b64_tr_b16 v[222:223], v190 offset:2656
	ds_read_b64_tr_b16 v[226:227], v190 offset:2688
	s_branch .Lum2_join

; #define LAS __attribute__((address_space(3)))
; DI void mlstm_phase(LAS unsigned char* lds, const bf16_t* proj, const float* gates, bf16_t* Hfw, bf16_t* Hbw, int G, int bid) {
;     ...
;                 for (int jj = 0; jj < 4; ++jj) {
;                     if (2 * jj <= wid) {
;                         f32x4 s0 = {0.f, 0.f, 0.f, 0.f}, s1 = s0;
;                         bf16x8 k0[4], k1[4], vfr[5];
;                         const int vr = 32 * jj + 4 * fq + (fr >> 2);
; #pragma unroll
;                         for (int ks = 0; ks < 4; ++ks) {
;                             k0[ks] = *(const LAS bf16x8*)(Ks + (32 * jj + fr) * MQ_STRIDE + ks * 64 + fq * 16);
;                             k1[ks] = *(const LAS bf16x8*)(Ks + (32 * jj + 16 + fr) * MQ_STRIDE + ks * 64 + fq * 16);
;                         }
;                         __builtin_amdgcn_sched_barrier(0);
; #pragma unroll
;                         for (int ks = 0; ks < 4; ++ks) {
;                             s0 = __builtin_amdgcn_mfma_f32_16x16x32_bf16(k0[ks], qf[ks], s0, 0, 0, 0);
;                             s1 = __builtin_amdgcn_mfma_f32_16x16x32_bf16(k1[ks], qf[ks], s1, 0, 0, 0);
;                         }
;                         __builtin_amdgcn_sched_barrier(0);
; #pragma unroll
;                         for (int dt = 0; dt < 5; ++dt) vfr[dt] = tr_pair(Vs + vr * MV_STRIDE + (16 * dt + 4 * (fr & 3)) * 2, Vs + (vr + 16) * MV_STRIDE + (16 * dt + 4 * (fr & 3)) * 2);
;                         const f32x4 a0 = *(const LAS f32x4*)(sa + 32 * jj + 4 * fq), a1 = *(const LAS f32x4*)(sa + 32 * jj + 16 + 4 * fq);
; #pragma unroll
;                         for (int i = 0; i < 4; ++i) {
;                             const int sA = 32 * jj + 4 * fq + i, sB = sA + 16;
;                             s0[i] = (sA <= t) ? s0[i] * __expf(a0[i] - Mt) : 0.f;
;                             s1[i] = (sB <= t) ? s1[i] * __expf(a1[i] - Mt) : 0.f;
;                         }
;                         u32x4 w; w.x = pk2(s0[0], s0[1]); w.y = pk2(s0[2], s0[3]); w.z = pk2(s1[0], s1[1]); w.w = pk2(s1[2], s1[3]);
;                         const bf16x8 pb = __builtin_bit_cast(bf16x8, w);
; #pragma unroll
;                         for (int dt = 0; dt < 5; ++dt) nacc[dt] = __builtin_amdgcn_mfma_f32_16x16x32_bf16(vfr[dt], pb, nacc[dt], 0, 0, 0);
;                     }
.LBB0_848:
	ds_read_b128 v[126:129], v206 offset:43520
	ds_read_b128 v[212:215], v206 offset:43584
	ds_read_b128 v[216:219], v206 offset:47872
	ds_read_b128 v[220:223], v206 offset:47936
	ds_read_b128 v[224:227], v206 offset:43648
	ds_read_b128 v[228:231], v206 offset:43712
	ds_read_b128 v[232:235], v206 offset:48000
	ds_read_b128 v[236:239], v206 offset:48064
	ds_read_b128 v[240:243], v0 offset:128
	ds_read_b64_tr_b16 v[246:247], v188 offset:2560
	ds_read_b64_tr_b16 v[244:245], v188
	ds_read_b128 v[248:251], v0 offset:192
	s_waitcnt lgkmcnt(11)
	v_mfma_f32_16x16x32_bf16 v[126:129], v[126:129], v[116:119], 0
	v_readlane_b32 s92, v255, 12
	s_waitcnt lgkmcnt(3)
	v_sub_f32_e32 v125, v240, v2
	v_mul_f32_e32 v125, 0x3fb8aa3b, v125
	v_exp_f32_e32 v240, v125
	s_waitcnt lgkmcnt(0)
	v_sub_f32_e32 v125, v248, v2
	v_mfma_f32_16x16x32_bf16 v[126:129], v[212:215], v[112:115], v[126:129]
	v_mul_f32_e32 v125, 0x3fb8aa3b, v125
	v_exp_f32_e32 v248, v125
	v_sub_f32_e32 v125, v241, v2
	v_mul_f32_e32 v125, 0x3fb8aa3b, v125
	v_mfma_f32_16x16x32_bf16 v[216:219], v[216:219], v[116:119], 0
	v_exp_f32_e32 v241, v125
	v_sub_f32_e32 v125, v249, v2
	v_mul_f32_e32 v125, 0x3fb8aa3b, v125
	v_mfma_f32_16x16x32_bf16 v[126:129], v[224:227], v[108:111], v[126:129]
	v_exp_f32_e32 v249, v125
	v_sub_f32_e32 v125, v242, v2
	v_mul_f32_e32 v125, 0x3fb8aa3b, v125
	v_mfma_f32_16x16x32_bf16 v[212:215], v[220:223], v[112:115], v[216:219]
	v_readlane_b32 s93, v255, 13
	s_nop 1
	v_exp_f32_e32 v216, v125
	v_sub_f32_e32 v125, v250, v2
	v_mfma_f32_16x16x32_bf16 v[126:129], v[228:231], v[100:103], v[126:129]
	v_mul_f32_e32 v125, 0x3fb8aa3b, v125
	v_exp_f32_e32 v218, v125
	v_sub_f32_e32 v125, v243, v2
	v_mul_f32_e32 v125, 0x3fb8aa3b, v125
	v_mfma_f32_16x16x32_bf16 v[212:215], v[232:235], v[108:111], v[212:215]
	v_exp_f32_e32 v217, v125
	v_sub_f32_e32 v125, v251, v2
	v_mul_f32_e32 v125, 0x3fb8aa3b, v125
	v_pk_mul_f32 v[126:127], v[126:127], v[240:241]
	v_exp_f32_e32 v219, v125
	s_and_b64 vcc, exec, s[28:29]
	s_cbranch_vccnz .Lum1
	v_cvt_pk_bf16_f32 v125, v126, v127
	v_cndmask_b32_e64 v126, v125, 0, s[92:93]
	v_readlane_b32 s92, v255, 10
	v_mfma_f32_16x16x32_bf16 v[212:215], v[236:239], v[100:103], v[212:215]
	v_lshrrev_b32_e32 v125, 16, v125
	v_readlane_b32 s93, v255, 11
	v_pk_mul_f32 v[128:129], v[128:129], v[216:217]
	s_nop 0
	v_cndmask_b32_e64 v125, v125, 0, s[92:93]
	v_perm_b32 v126, v125, v126, s45
	v_cvt_pk_bf16_f32 v125, v128, v129
	v_readlane_b32 s92, v255, 18
	v_cndmask_b32_e64 v127, v125, 0, s[52:53]
	v_lshrrev_b32_e32 v125, 16, v125
	v_readlane_b32 s93, v255, 19
	v_pk_mul_f32 v[212:213], v[212:213], v[248:249]
	v_pk_mul_f32 v[214:215], v[214:215], v[218:219]
	v_cndmask_b32_e64 v125, v125, 0, s[92:93]
	v_readlane_b32 s92, v255, 16
	v_perm_b32 v127, v125, v127, s45
	v_cvt_pk_bf16_f32 v125, v212, v213
	v_readlane_b32 s93, v255, 17
	s_nop 1
	v_cndmask_b32_e64 v128, v125, 0, s[92:93]
	v_readlane_b32 s92, v255, 14
	v_lshrrev_b32_e32 v125, 16, v125
	v_readlane_b32 s93, v255, 15
	s_nop 1
	v_cndmask_b32_e64 v125, v125, 0, s[92:93]
	v_perm_b32 v128, v125, v128, s45
	v_cvt_pk_bf16_f32 v125, v214, v215
	ds_read_b64_tr_b16 v[214:215], v188 offset:2592
	ds_read_b64_tr_b16 v[212:213], v188 offset:32
	ds_read_b64_tr_b16 v[216:217], v188 offset:64
	ds_read_b64_tr_b16 v[220:221], v188 offset:96
	ds_read_b64_tr_b16 v[218:219], v188 offset:2624
	ds_read_b64_tr_b16 v[224:225], v188 offset:128
	ds_read_b64_tr_b16 v[222:223], v188 offset:2656
	ds_read_b64_tr_b16 v[226:227], v188 offset:2688
	v_cndmask_b32_e64 v129, v125, 0, s[56:57]
	v_lshrrev_b32_e32 v125, 16, v125
	v_cndmask_b32_e64 v125, v125, 0, s[54:55]
	v_perm_b32 v129, v125, v129, s45
.Lum1_join:
	s_nop 1
	v_mfma_f32_16x16x32_bf16 v[84:87], v[244:247], v[126:129], v[84:87]
	s_waitcnt lgkmcnt(6)
	v_mfma_f32_16x16x32_bf16 v[88:91], v[212:215], v[126:129], v[88:91]
	s_waitcnt lgkmcnt(3)
	v_mfma_f32_16x16x32_bf16 v[92:95], v[216:219], v[126:129], v[92:95]
	s_waitcnt lgkmcnt(1)
	v_mfma_f32_16x16x32_bf16 v[96:99], v[220:223], v[126:129], v[96:99]
	s_waitcnt lgkmcnt(0)
	v_mfma_f32_16x16x32_bf16 v[104:107], v[224:227], v[126:129], v[104:107]
	s_andn2_b64 vcc, exec, s[28:29]
	s_cbranch_vccz .LBB0_846
